# barrier leader no longer bumps the per-XCC generation word (nobody reads it since all workgroups poll the cross-XCC generation)
# speedup vs baseline: 1.0011x; 1.0011x over previous
.LBB0_129:
	s_or_b64 exec, exec, s[8:9]
	s_mov_b64 s[8:9], exec
	v_mbcnt_lo_u32_b32 v0, s8, 0
	v_mbcnt_hi_u32_b32 v0, s9, v0
	v_cmp_eq_u32_e32 vcc, 0, v0
	s_waitcnt vmcnt(0)
	buffer_inv sc1
	s_and_saveexec_b64 s[10:11], vcc
	s_cbranch_execz .LBB0_131
	s_bcnt1_i32_b64 s3, s[8:9]
	v_mov_b32_e32 v0, 0x2000
	v_mov_b32_e32 v1, s3
	s_nop 0

.LBB0_202:
	s_or_b64 exec, exec, s[6:7]
	s_mov_b64 s[6:7], exec
	v_mbcnt_lo_u32_b32 v0, s6, 0
	v_mbcnt_hi_u32_b32 v0, s7, v0
	v_cmp_eq_u32_e32 vcc, 0, v0
	s_waitcnt vmcnt(0)
	buffer_inv sc1
	s_and_saveexec_b64 s[8:9], vcc
	s_cbranch_execz .LBB0_204
	s_bcnt1_i32_b64 s6, s[6:7]
	v_mov_b32_e32 v0, 0x2000
	v_mov_b32_e32 v1, s6
	s_nop 0

.LBB0_1317:
	s_or_b64 exec, exec, s[8:9]
	s_mov_b64 s[8:9], exec
	v_mbcnt_lo_u32_b32 v0, s8, 0
	v_mbcnt_hi_u32_b32 v0, s9, v0
	v_cmp_eq_u32_e32 vcc, 0, v0
	s_waitcnt vmcnt(0)
	buffer_inv sc1
	s_and_saveexec_b64 s[10:11], vcc
	s_cbranch_execz .LBB0_1319
	s_bcnt1_i32_b64 s8, s[8:9]
	v_mov_b32_e32 v0, 0x2000
	v_mov_b32_e32 v1, s8
	s_nop 0

.LBB0_2736:
	s_or_b64 exec, exec, s[6:7]
	s_mov_b64 s[6:7], exec
	v_mbcnt_lo_u32_b32 v0, s6, 0
	v_mbcnt_hi_u32_b32 v0, s7, v0
	v_cmp_eq_u32_e32 vcc, 0, v0
	s_waitcnt vmcnt(0)
	buffer_inv sc1
	s_and_saveexec_b64 s[10:11], vcc
	s_cbranch_execz .LBB0_2738
	s_bcnt1_i32_b64 s6, s[6:7]
	v_mov_b32_e32 v0, 0x2000
	v_mov_b32_e32 v1, s6
	s_nop 0

.LBB0_2845:
	s_or_b64 exec, exec, s[4:5]
	s_mov_b64 s[4:5], exec
	v_mbcnt_lo_u32_b32 v0, s4, 0
	v_mbcnt_hi_u32_b32 v0, s5, v0
	v_cmp_eq_u32_e32 vcc, 0, v0
	s_waitcnt vmcnt(0)
	buffer_inv sc1
	s_and_saveexec_b64 s[6:7], vcc
	s_cbranch_execz .LBB0_2847
	s_bcnt1_i32_b64 s4, s[4:5]
	v_mov_b32_e32 v0, 0x2000
	v_mov_b32_e32 v1, s4
	s_nop 0
